# diff-attn exit flag tests the bound of the next tile so the walk stops at the same tile as before the flag read was moved ahead of the barrier
# speedup vs baseline: 1.0118x; 1.0118x over previous
.LBB0_241:
	s_add_i32 s2, s99, 0x80
	v_cvt_f32_i32_e32 v238, s2
	v_fma_f32 v238, v145, v238, v119
	v_sub_f32_e32 v238, v238, v120
	v_cmp_gt_f32_e32 vcc, s85, v238
	s_cmp_eq_u64 vcc, exec
	s_cselect_b64 s[8:9], -1, 0
	v_cndmask_b32_e64 v238, 0, 1, s[8:9]
	s_and_saveexec_b64 s[8:9], s[6:7]
	s_cbranch_execnz .LBB0_234
	s_branch .LBB0_235

.LBB0_253:
	s_add_i32 s10, s99, 0x40
	v_cvt_f32_i32_e32 v238, s10
	v_fma_f32 v238, v145, v238, v119
	v_sub_f32_e32 v238, v238, v120
	v_cmp_gt_f32_e32 vcc, s85, v238
	s_cmp_eq_u64 vcc, exec
	s_cselect_b64 s[10:11], -1, 0
	v_cndmask_b32_e64 v238, 0, 1, s[10:11]
	s_and_saveexec_b64 s[10:11], s[6:7]
	s_cbranch_execnz .LBB0_249
	s_branch .LBB0_250

.LBB0_270:
	s_add_i32 s3, s99, 0
	v_cvt_f32_i32_e32 v238, s3
	v_fma_f32 v238, v145, v238, v119
	v_sub_f32_e32 v238, v238, v120
	v_cmp_gt_f32_e32 vcc, s85, v238
	s_cmp_eq_u64 vcc, exec
	s_cselect_b64 s[8:9], -1, 0
	v_cndmask_b32_e64 v238, 0, 1, s[8:9]
	s_and_saveexec_b64 s[8:9], s[6:7]
	s_cbranch_execnz .LBB0_265
	s_branch .LBB0_266

.LBB0_285:
	s_add_i32 s2, s99, 0xffffffc0
	v_cvt_f32_i32_e32 v238, s2
	v_fma_f32 v238, v145, v238, v119
	v_sub_f32_e32 v238, v238, v120
	v_cmp_gt_f32_e32 vcc, s85, v238
	s_cmp_eq_u64 vcc, exec
	s_cselect_b64 s[2:3], -1, 0
	v_cndmask_b32_e64 v238, 0, 1, s[2:3]
	s_and_saveexec_b64 s[8:9], s[6:7]
	s_cbranch_execnz .LBB0_282
	s_branch .LBB0_283
